# MoBA step code motion: fast path and no-rescale route made fall-through, slow own-block path and rescale block out of line (fewer taken branches); on top of v55
# speedup vs baseline: 1.0111x; 1.0021x over previous
.LBB0_909:
	s_lshr_b32 s54, s13, 2
	s_cmp_ge_i32 s54, s93
	s_cselect_b64 s[50:51], -1, 0
	s_cbranch_scc1 .Lme_slow
	v_lshrrev_b32_e32 v48, s54, v146
	v_and_b32_e32 v48, 1, v48
	v_cmp_eq_u32_e32 vcc, 1, v48
	s_cbranch_vccz .LBB0_921
	v_add_u32_e32 v124, v159, v132
	s_nop 0
	v_cndmask_b32_e64 v48, v210, 0, vcc
	v_pk_add_f32 v[62:63], v[46:47], v[48:49] op_sel_hi:[1,0]
	v_pk_add_f32 v[60:61], v[44:45], v[48:49] op_sel_hi:[1,0]
	v_pk_add_f32 v[58:59], v[42:43], v[48:49] op_sel_hi:[1,0]
	v_pk_add_f32 v[56:57], v[40:41], v[48:49] op_sel_hi:[1,0]
	v_pk_add_f32 v[54:55], v[38:39], v[48:49] op_sel_hi:[1,0]
	v_pk_add_f32 v[52:53], v[36:37], v[48:49] op_sel_hi:[1,0]
	v_pk_add_f32 v[50:51], v[34:35], v[48:49] op_sel_hi:[1,0]
	v_pk_add_f32 v[48:49], v[32:33], v[48:49] op_sel_hi:[1,0]
	ds_read_b128 v[112:115], v124
	ds_read_b128 v[116:119], v124 offset:32
	s_waitcnt lgkmcnt(1)
	v_mfma_f32_32x32x16_bf16 v[64:79], v[112:115], v[80:83], v[48:63]
	ds_read_b128 v[112:115], v124 offset:4608
	ds_read_b128 v[120:123], v124 offset:4640
	s_waitcnt lgkmcnt(1)
	v_mfma_f32_32x32x16_bf16 v[48:63], v[112:115], v[80:83], v[48:63]
	v_mfma_f32_32x32x16_bf16 v[64:79], v[116:119], v[84:87], v[64:79]
	ds_read_b128 v[112:115], v124 offset:64
	ds_read_b128 v[116:119], v124 offset:96
	s_waitcnt lgkmcnt(2)
	v_mfma_f32_32x32x16_bf16 v[48:63], v[120:123], v[84:87], v[48:63]
	s_waitcnt lgkmcnt(1)
	v_mfma_f32_32x32x16_bf16 v[64:79], v[112:115], v[88:91], v[64:79]
	ds_read_b128 v[112:115], v124 offset:4672
	ds_read_b128 v[214:217], v124 offset:4704
	s_waitcnt lgkmcnt(1)
	v_mfma_f32_32x32x16_bf16 v[48:63], v[112:115], v[88:91], v[48:63]
	v_mfma_f32_32x32x16_bf16 v[64:79], v[116:119], v[92:95], v[64:79]
	ds_read_b64_tr_b16 v[120:121], v160 offset:18432
	ds_read_b64_tr_b16 v[122:123], v160 offset:19968
	ds_read_b64_tr_b16 v[114:115], v160 offset:20032
	ds_read_b64_tr_b16 v[112:113], v160 offset:18496
	ds_read_b64_tr_b16 v[124:125], v160 offset:21504
	ds_read_b64_tr_b16 v[126:127], v160 offset:23040
	ds_read_b64_tr_b16 v[118:119], v160 offset:23104
	ds_read_b64_tr_b16 v[116:117], v160 offset:21568
	s_waitcnt lgkmcnt(8)
	v_mfma_f32_32x32x16_bf16 v[48:63], v[214:217], v[92:95], v[48:63]
.LBB0_918:
	s_nop 4
	v_max3_f32 v213, v64, v65, v66
	v_max3_f32 v214, v67, v68, v69
	v_max3_f32 v213, v213, v70, v71
	v_max3_f32 v214, v214, v72, v73
	v_max3_f32 v213, v213, v74, v75
	v_max3_f32 v214, v214, v76, v77
	v_max3_f32 v213, v213, v78, v79
	v_max3_f32 v214, v214, v48, v49
	v_max3_f32 v213, v213, v50, v51
	v_max3_f32 v214, v214, v52, v53
	v_max3_f32 v213, v213, v54, v55
	v_max3_f32 v214, v214, v56, v57
	v_max3_f32 v213, v213, v58, v59
	v_max3_f32 v214, v214, v60, v61
	v_max3_f32 v213, v213, v62, v63
	v_max_f32_e32 v213, v213, v214
	v_mov_b32_e32 v214, v213
	s_nop 1
	v_permlane32_swap_b32_e32 v214, v213
	v_max_f32_e32 v213, v213, v214
	v_cmp_lt_f32_e32 vcc, s92, v213
	s_cbranch_vccnz .Lme_resc

.LBB0_924:
	s_cmp_eq_u64 s[50:51], 0
	s_cbranch_scc0 .Lmo_slow
	v_lshrrev_b32_e32 v48, s54, v146
	v_and_b32_e32 v48, 1, v48
	v_cmp_eq_u32_e32 vcc, 1, v48
	s_cbranch_vccz .LBB0_936
	v_add_u32_e32 v124, v159, v132
	s_nop 0
	v_cndmask_b32_e64 v48, v210, 0, vcc
	v_pk_add_f32 v[62:63], v[46:47], v[48:49] op_sel_hi:[1,0]
	v_pk_add_f32 v[60:61], v[44:45], v[48:49] op_sel_hi:[1,0]
	v_pk_add_f32 v[58:59], v[42:43], v[48:49] op_sel_hi:[1,0]
	v_pk_add_f32 v[56:57], v[40:41], v[48:49] op_sel_hi:[1,0]
	v_pk_add_f32 v[54:55], v[38:39], v[48:49] op_sel_hi:[1,0]
	v_pk_add_f32 v[52:53], v[36:37], v[48:49] op_sel_hi:[1,0]
	v_pk_add_f32 v[50:51], v[34:35], v[48:49] op_sel_hi:[1,0]
	v_pk_add_f32 v[48:49], v[32:33], v[48:49] op_sel_hi:[1,0]
	ds_read_b128 v[112:115], v124 offset:9216
	ds_read_b128 v[116:119], v124 offset:9248
	s_waitcnt lgkmcnt(1)
	v_mfma_f32_32x32x16_bf16 v[64:79], v[112:115], v[80:83], v[48:63]
	ds_read_b128 v[112:115], v124 offset:13824
	ds_read_b128 v[120:123], v124 offset:13856
	s_waitcnt lgkmcnt(1)
	v_mfma_f32_32x32x16_bf16 v[48:63], v[112:115], v[80:83], v[48:63]
	v_mfma_f32_32x32x16_bf16 v[64:79], v[116:119], v[84:87], v[64:79]
	ds_read_b128 v[112:115], v124 offset:9280
	ds_read_b128 v[116:119], v124 offset:9312
	s_waitcnt lgkmcnt(2)
	v_mfma_f32_32x32x16_bf16 v[48:63], v[120:123], v[84:87], v[48:63]
	s_waitcnt lgkmcnt(1)
	v_mfma_f32_32x32x16_bf16 v[64:79], v[112:115], v[88:91], v[64:79]
	ds_read_b128 v[112:115], v124 offset:13888
	ds_read_b128 v[212:215], v124 offset:13920
	s_waitcnt lgkmcnt(1)
	v_mfma_f32_32x32x16_bf16 v[48:63], v[112:115], v[88:91], v[48:63]
	v_mfma_f32_32x32x16_bf16 v[64:79], v[116:119], v[92:95], v[64:79]
	ds_read_b64_tr_b16 v[120:121], v160 offset:30720
	ds_read_b64_tr_b16 v[122:123], v160 offset:32256
	ds_read_b64_tr_b16 v[114:115], v160 offset:32320
	ds_read_b64_tr_b16 v[112:113], v160 offset:30784
	ds_read_b64_tr_b16 v[124:125], v160 offset:33792
	ds_read_b64_tr_b16 v[126:127], v160 offset:35328
	ds_read_b64_tr_b16 v[118:119], v160 offset:35392
	ds_read_b64_tr_b16 v[116:117], v160 offset:33856
	s_waitcnt lgkmcnt(8)
	v_mfma_f32_32x32x16_bf16 v[48:63], v[212:215], v[92:95], v[48:63]
.LBB0_933:
	s_nop 4
	v_max3_f32 v149, v64, v65, v66
	v_max3_f32 v212, v67, v68, v69
	v_max3_f32 v149, v149, v70, v71
	v_max3_f32 v212, v212, v72, v73
	v_max3_f32 v149, v149, v74, v75
	v_max3_f32 v212, v212, v76, v77
	v_max3_f32 v149, v149, v78, v79
	v_max3_f32 v212, v212, v48, v49
	v_max3_f32 v149, v149, v50, v51
	v_max3_f32 v212, v212, v52, v53
	v_max3_f32 v149, v149, v54, v55
	v_max3_f32 v212, v212, v56, v57
	v_max3_f32 v149, v149, v58, v59
	v_max3_f32 v212, v212, v60, v61
	v_max3_f32 v149, v149, v62, v63
	v_max_f32_e32 v149, v149, v212
	v_mov_b32_e32 v212, v149
	s_nop 1
	v_permlane32_swap_b32_e32 v212, v149
	v_max_f32_e32 v149, v149, v212
	v_cmp_lt_f32_e32 vcc, s92, v149
	s_cbranch_vccnz .Lmo_resc

.Lme_slow:
	s_mov_b64 s[14:15], -1
	s_and_b64 vcc, exec, s[50:51]
	s_mov_b64 s[4:5], -1
	s_cbranch_vccz .LBB0_911
	s_and_b32 s4, s3, 0x80
	v_subrev_u32_e32 v48, s4, v154
	v_min_i32_e32 v213, 63, v48
	s_mov_b64 s[4:5], 0

.LBB0_913:
	v_cmp_lt_i32_e32 vcc, -1, v213
	s_and_b64 s[4:5], s[14:15], vcc
	v_cndmask_b32_e64 v48, 0, 1, s[4:5]
	v_cmp_ne_u32_e32 vcc, 0, v48
	s_cbranch_vccz .LBB0_921
	v_add_u32_e32 v124, v159, v132
	v_cmp_lt_i32_e32 vcc, 62, v213
	s_xor_b64 s[52:53], s[4:5], -1
	ds_read_b128 v[112:115], v124
	ds_read_b128 v[116:119], v124 offset:32
	s_or_b64 s[16:17], vcc, s[52:53]
	v_cndmask_b32_e64 v48, 0, 1, s[16:17]
	s_and_b64 s[14:15], s[14:15], vcc
	v_cmp_ne_u32_e32 vcc, 0, v48
	s_cmp_lg_u64 vcc, exec
	s_cselect_b64 s[16:17], -1, 0
	s_or_b64 s[14:15], s[14:15], s[16:17]
	v_cndmask_b32_e64 v48, v210, 0, s[14:15]
	v_pk_add_f32 v[62:63], v[46:47], v[48:49] op_sel_hi:[1,0]
	v_pk_add_f32 v[60:61], v[44:45], v[48:49] op_sel_hi:[1,0]
	v_pk_add_f32 v[58:59], v[42:43], v[48:49] op_sel_hi:[1,0]
	v_pk_add_f32 v[56:57], v[40:41], v[48:49] op_sel_hi:[1,0]
	v_pk_add_f32 v[54:55], v[38:39], v[48:49] op_sel_hi:[1,0]
	v_pk_add_f32 v[52:53], v[36:37], v[48:49] op_sel_hi:[1,0]
	v_pk_add_f32 v[50:51], v[34:35], v[48:49] op_sel_hi:[1,0]
	v_pk_add_f32 v[48:49], v[32:33], v[48:49] op_sel_hi:[1,0]
	s_cmp_eq_u64 vcc, exec
	s_waitcnt lgkmcnt(1)
	v_mfma_f32_32x32x16_bf16 v[64:79], v[112:115], v[80:83], v[48:63]
	ds_read_b128 v[112:115], v124 offset:4608
	ds_read_b128 v[120:123], v124 offset:4640
	s_waitcnt lgkmcnt(1)
	v_mfma_f32_32x32x16_bf16 v[48:63], v[112:115], v[80:83], v[48:63]
	v_mfma_f32_32x32x16_bf16 v[64:79], v[116:119], v[84:87], v[64:79]
	ds_read_b128 v[112:115], v124 offset:64
	ds_read_b128 v[116:119], v124 offset:96
	s_waitcnt lgkmcnt(2)
	v_mfma_f32_32x32x16_bf16 v[48:63], v[120:123], v[84:87], v[48:63]
	s_waitcnt lgkmcnt(1)
	v_mfma_f32_32x32x16_bf16 v[64:79], v[112:115], v[88:91], v[64:79]
	ds_read_b128 v[112:115], v124 offset:4672
	ds_read_b128 v[214:217], v124 offset:4704
	s_waitcnt lgkmcnt(1)
	v_mfma_f32_32x32x16_bf16 v[48:63], v[112:115], v[88:91], v[48:63]
	v_mfma_f32_32x32x16_bf16 v[64:79], v[116:119], v[92:95], v[64:79]
	ds_read_b64_tr_b16 v[120:121], v160 offset:18432
	ds_read_b64_tr_b16 v[122:123], v160 offset:19968
	ds_read_b64_tr_b16 v[114:115], v160 offset:20032
	ds_read_b64_tr_b16 v[112:113], v160 offset:18496
	ds_read_b64_tr_b16 v[124:125], v160 offset:21504
	ds_read_b64_tr_b16 v[126:127], v160 offset:23040
	ds_read_b64_tr_b16 v[118:119], v160 offset:23104
	ds_read_b64_tr_b16 v[116:117], v160 offset:21568
	s_waitcnt lgkmcnt(8)
	v_mfma_f32_32x32x16_bf16 v[48:63], v[214:217], v[92:95], v[48:63]
	s_cbranch_scc1 .LBB0_918
	v_cmp_le_u32_e64 s[14:15], v161, v213
	v_cmp_le_u32_e64 s[16:17], v162, v213
	v_cmp_le_u32_e64 s[18:19], v164, v213
	v_cmp_le_u32_e64 s[20:21], v166, v213
	v_cmp_le_u32_e64 s[22:23], v168, v213
	v_cmp_le_u32_e64 s[24:25], v170, v213
	v_cmp_le_u32_e64 s[26:27], v172, v213
	v_cmp_le_u32_e64 s[28:29], v174, v213
	v_cmp_le_u32_e64 s[30:31], v176, v213
	v_cmp_le_u32_e64 s[34:35], v178, v213
	v_cmp_le_u32_e64 s[36:37], v180, v213
	v_cmp_le_u32_e64 s[38:39], v182, v213
	v_cmp_le_u32_e64 s[40:41], v184, v213
	v_cmp_le_u32_e64 s[42:43], v186, v213
	v_cmp_le_u32_e64 s[44:45], v189, v213
	s_and_b64 s[14:15], s[4:5], s[14:15]
	s_and_b64 s[16:17], s[4:5], s[16:17]
	s_and_b64 s[18:19], s[4:5], s[18:19]
	s_and_b64 s[20:21], s[4:5], s[20:21]
	s_and_b64 s[22:23], s[4:5], s[22:23]
	s_and_b64 s[24:25], s[4:5], s[24:25]
	s_and_b64 s[26:27], s[4:5], s[26:27]
	s_and_b64 s[28:29], s[4:5], s[28:29]
	s_and_b64 s[30:31], s[4:5], s[30:31]
	s_and_b64 s[34:35], s[4:5], s[34:35]
	s_and_b64 s[36:37], s[4:5], s[36:37]
	s_and_b64 s[38:39], s[4:5], s[38:39]
	s_and_b64 s[40:41], s[4:5], s[40:41]
	s_and_b64 s[42:43], s[4:5], s[42:43]
	s_and_b64 s[44:45], s[4:5], s[44:45]
	v_cmp_gt_u32_e64 s[46:47], v191, v213
	v_cmp_le_u32_e32 vcc, v138, v213
	v_cndmask_b32_e64 v48, v210, v48, s[14:15]
	v_cmp_lt_u32_e64 s[14:15], v138, v213
	v_cndmask_b32_e64 v49, v210, v49, s[16:17]
	v_cmp_le_u32_e64 s[16:17], v163, v213
	v_cndmask_b32_e64 v50, v210, v50, s[18:19]
	v_cmp_le_u32_e64 s[18:19], v165, v213
	v_cndmask_b32_e64 v51, v210, v51, s[20:21]
	v_cmp_le_u32_e64 s[20:21], v167, v213
	v_cndmask_b32_e64 v52, v210, v52, s[22:23]
	v_cmp_le_u32_e64 s[22:23], v169, v213
	v_cndmask_b32_e64 v53, v210, v53, s[24:25]
	v_cmp_le_u32_e64 s[24:25], v171, v213
	v_cndmask_b32_e64 v54, v210, v54, s[26:27]
	v_cmp_le_u32_e64 s[26:27], v173, v213
	v_cndmask_b32_e64 v55, v210, v55, s[28:29]
	v_cmp_le_u32_e64 s[28:29], v175, v213
	v_cndmask_b32_e64 v56, v210, v56, s[30:31]
	v_cmp_le_u32_e64 s[30:31], v177, v213
	v_cndmask_b32_e64 v57, v210, v57, s[34:35]
	v_cmp_le_u32_e64 s[34:35], v179, v213
	v_cndmask_b32_e64 v58, v210, v58, s[36:37]
	v_cmp_le_u32_e64 s[36:37], v181, v213
	v_cndmask_b32_e64 v59, v210, v59, s[38:39]
	v_cmp_le_u32_e64 s[38:39], v183, v213
	v_cndmask_b32_e64 v60, v210, v60, s[40:41]
	v_cmp_le_u32_e64 s[40:41], v185, v213
	v_cndmask_b32_e64 v61, v210, v61, s[42:43]
	v_cmp_le_u32_e64 s[42:43], v187, v213
	v_cndmask_b32_e64 v62, v210, v62, s[44:45]
	v_cmp_le_u32_e64 s[44:45], v190, v213
	s_or_b64 s[52:53], s[52:53], s[46:47]
	s_and_saveexec_b64 s[46:47], s[52:53]
	v_mov_b32_e32 v63, s33
	s_or_b64 exec, exec, s[46:47]
	s_and_b64 vcc, s[4:5], vcc
	v_cndmask_b32_e32 v64, v210, v64, vcc
	s_and_b64 vcc, s[4:5], s[14:15]
	v_cndmask_b32_e32 v65, v210, v65, vcc
	s_and_b64 vcc, s[4:5], s[16:17]
	v_cndmask_b32_e32 v66, v210, v66, vcc
	s_and_b64 vcc, s[4:5], s[18:19]
	v_cndmask_b32_e32 v67, v210, v67, vcc
	s_and_b64 vcc, s[4:5], s[20:21]
	v_cndmask_b32_e32 v68, v210, v68, vcc
	s_and_b64 vcc, s[4:5], s[22:23]
	v_cndmask_b32_e32 v69, v210, v69, vcc
	s_and_b64 vcc, s[4:5], s[24:25]
	v_cndmask_b32_e32 v70, v210, v70, vcc
	s_and_b64 vcc, s[4:5], s[26:27]
	v_cndmask_b32_e32 v71, v210, v71, vcc
	s_and_b64 vcc, s[4:5], s[28:29]
	v_cndmask_b32_e32 v72, v210, v72, vcc
	s_and_b64 vcc, s[4:5], s[30:31]
	v_cndmask_b32_e32 v73, v210, v73, vcc
	s_and_b64 vcc, s[4:5], s[34:35]
	v_cndmask_b32_e32 v74, v210, v74, vcc
	s_and_b64 vcc, s[4:5], s[36:37]
	v_cndmask_b32_e32 v75, v210, v75, vcc
	s_and_b64 vcc, s[4:5], s[38:39]
	v_cndmask_b32_e32 v76, v210, v76, vcc
	s_and_b64 vcc, s[4:5], s[40:41]
	v_cndmask_b32_e32 v77, v210, v77, vcc
	s_and_b64 vcc, s[4:5], s[42:43]
	v_cndmask_b32_e32 v78, v210, v78, vcc
	s_and_b64 vcc, s[4:5], s[44:45]
	v_cndmask_b32_e32 v79, v210, v79, vcc
	s_branch .LBB0_918
.Lme_resc:
	v_max_f32_e32 v32, v213, v213
	v_max_f32_e32 v34, 0, v32
	v_exp_f32_e64 v36, -v34
	v_add_f32_e32 v148, v148, v34
	v_xor_b32_e32 v32, 0x80000000, v148
	v_pk_add_f32 v[64:65], v[64:65], v[34:35] op_sel_hi:[1,0] neg_lo:[0,1] neg_hi:[0,1]
	v_mul_f32_e32 v147, v147, v36
	v_pk_add_f32 v[48:49], v[48:49], v[34:35] op_sel_hi:[1,0] neg_lo:[0,1] neg_hi:[0,1]
	v_pk_add_f32 v[66:67], v[66:67], v[34:35] op_sel_hi:[1,0] neg_lo:[0,1] neg_hi:[0,1]
	v_pk_add_f32 v[50:51], v[50:51], v[34:35] op_sel_hi:[1,0] neg_lo:[0,1] neg_hi:[0,1]
	v_pk_add_f32 v[68:69], v[68:69], v[34:35] op_sel_hi:[1,0] neg_lo:[0,1] neg_hi:[0,1]
	v_pk_add_f32 v[52:53], v[52:53], v[34:35] op_sel_hi:[1,0] neg_lo:[0,1] neg_hi:[0,1]
	v_pk_add_f32 v[70:71], v[70:71], v[34:35] op_sel_hi:[1,0] neg_lo:[0,1] neg_hi:[0,1]
	v_pk_add_f32 v[54:55], v[54:55], v[34:35] op_sel_hi:[1,0] neg_lo:[0,1] neg_hi:[0,1]
	v_pk_add_f32 v[72:73], v[72:73], v[34:35] op_sel_hi:[1,0] neg_lo:[0,1] neg_hi:[0,1]
	v_pk_add_f32 v[56:57], v[56:57], v[34:35] op_sel_hi:[1,0] neg_lo:[0,1] neg_hi:[0,1]
	v_pk_add_f32 v[74:75], v[74:75], v[34:35] op_sel_hi:[1,0] neg_lo:[0,1] neg_hi:[0,1]
	v_pk_add_f32 v[58:59], v[58:59], v[34:35] op_sel_hi:[1,0] neg_lo:[0,1] neg_hi:[0,1]
	v_pk_add_f32 v[76:77], v[76:77], v[34:35] op_sel_hi:[1,0] neg_lo:[0,1] neg_hi:[0,1]
	v_pk_add_f32 v[60:61], v[60:61], v[34:35] op_sel_hi:[1,0] neg_lo:[0,1] neg_hi:[0,1]
	v_pk_add_f32 v[78:79], v[78:79], v[34:35] op_sel_hi:[1,0] neg_lo:[0,1] neg_hi:[0,1]
	v_pk_add_f32 v[62:63], v[62:63], v[34:35] op_sel_hi:[1,0] neg_lo:[0,1] neg_hi:[0,1]
	v_pk_mul_f32 v[14:15], v[14:15], v[36:37] op_sel_hi:[1,0]
	v_pk_mul_f32 v[12:13], v[12:13], v[36:37] op_sel_hi:[1,0]
	v_pk_mul_f32 v[10:11], v[10:11], v[36:37] op_sel_hi:[1,0]
	v_pk_mul_f32 v[8:9], v[8:9], v[36:37] op_sel_hi:[1,0]
	v_pk_mul_f32 v[6:7], v[6:7], v[36:37] op_sel_hi:[1,0]
	v_pk_mul_f32 v[4:5], v[4:5], v[36:37] op_sel_hi:[1,0]
	v_pk_mul_f32 v[2:3], v[2:3], v[36:37] op_sel_hi:[1,0]
	v_pk_mul_f32 v[0:1], v[0:1], v[36:37] op_sel_hi:[1,0]
	v_pk_mul_f32 v[30:31], v[30:31], v[36:37] op_sel_hi:[1,0]
	v_pk_mul_f32 v[28:29], v[28:29], v[36:37] op_sel_hi:[1,0]
	v_pk_mul_f32 v[26:27], v[26:27], v[36:37] op_sel_hi:[1,0]
	v_pk_mul_f32 v[24:25], v[24:25], v[36:37] op_sel_hi:[1,0]
	v_pk_mul_f32 v[22:23], v[22:23], v[36:37] op_sel_hi:[1,0]
	v_pk_mul_f32 v[20:21], v[20:21], v[36:37] op_sel_hi:[1,0]
	v_pk_mul_f32 v[18:19], v[18:19], v[36:37] op_sel_hi:[1,0]
	v_pk_mul_f32 v[16:17], v[16:17], v[36:37] op_sel_hi:[1,0]
	v_mov_b32_e32 v33, v32
	v_mov_b32_e32 v34, v32
	v_mov_b32_e32 v35, v32
	v_mov_b32_e32 v36, v32
	v_mov_b32_e32 v37, v32
	v_mov_b32_e32 v38, v32
	v_mov_b32_e32 v39, v32
	v_mov_b32_e32 v40, v32
	v_mov_b32_e32 v41, v32
	v_mov_b32_e32 v42, v32
	v_mov_b32_e32 v43, v32
	v_mov_b32_e32 v44, v32
	v_mov_b32_e32 v45, v32
	v_mov_b32_e32 v46, v32
	v_mov_b32_e32 v47, v32
	s_branch .LBB0_920

.LBB0_928:
	v_cmp_lt_i32_e32 vcc, -1, v149
	s_and_b64 s[4:5], s[14:15], vcc
	v_cndmask_b32_e64 v48, 0, 1, s[4:5]
	v_cmp_ne_u32_e32 vcc, 0, v48
	s_cbranch_vccz .LBB0_936
	v_add_u32_e32 v124, v159, v132
	v_cmp_lt_i32_e32 vcc, 62, v149
	s_xor_b64 s[50:51], s[4:5], -1
	ds_read_b128 v[112:115], v124 offset:9216
	ds_read_b128 v[116:119], v124 offset:9248
	s_or_b64 s[16:17], vcc, s[50:51]
	v_cndmask_b32_e64 v48, 0, 1, s[16:17]
	s_and_b64 s[14:15], s[14:15], vcc
	v_cmp_ne_u32_e32 vcc, 0, v48
	s_cmp_lg_u64 vcc, exec
	s_cselect_b64 s[16:17], -1, 0
	s_or_b64 s[14:15], s[14:15], s[16:17]
	v_cndmask_b32_e64 v48, v210, 0, s[14:15]
	v_pk_add_f32 v[62:63], v[46:47], v[48:49] op_sel_hi:[1,0]
	v_pk_add_f32 v[60:61], v[44:45], v[48:49] op_sel_hi:[1,0]
	v_pk_add_f32 v[58:59], v[42:43], v[48:49] op_sel_hi:[1,0]
	v_pk_add_f32 v[56:57], v[40:41], v[48:49] op_sel_hi:[1,0]
	v_pk_add_f32 v[54:55], v[38:39], v[48:49] op_sel_hi:[1,0]
	v_pk_add_f32 v[52:53], v[36:37], v[48:49] op_sel_hi:[1,0]
	v_pk_add_f32 v[50:51], v[34:35], v[48:49] op_sel_hi:[1,0]
	v_pk_add_f32 v[48:49], v[32:33], v[48:49] op_sel_hi:[1,0]
	s_cmp_eq_u64 vcc, exec
	s_waitcnt lgkmcnt(1)
	v_mfma_f32_32x32x16_bf16 v[64:79], v[112:115], v[80:83], v[48:63]
	ds_read_b128 v[112:115], v124 offset:13824
	ds_read_b128 v[120:123], v124 offset:13856
	s_waitcnt lgkmcnt(1)
	v_mfma_f32_32x32x16_bf16 v[48:63], v[112:115], v[80:83], v[48:63]
	v_mfma_f32_32x32x16_bf16 v[64:79], v[116:119], v[84:87], v[64:79]
	ds_read_b128 v[112:115], v124 offset:9280
	ds_read_b128 v[116:119], v124 offset:9312
	s_waitcnt lgkmcnt(2)
	v_mfma_f32_32x32x16_bf16 v[48:63], v[120:123], v[84:87], v[48:63]
	s_waitcnt lgkmcnt(1)
	v_mfma_f32_32x32x16_bf16 v[64:79], v[112:115], v[88:91], v[64:79]
	ds_read_b128 v[112:115], v124 offset:13888
	ds_read_b128 v[212:215], v124 offset:13920
	s_waitcnt lgkmcnt(1)
	v_mfma_f32_32x32x16_bf16 v[48:63], v[112:115], v[88:91], v[48:63]
	v_mfma_f32_32x32x16_bf16 v[64:79], v[116:119], v[92:95], v[64:79]
	ds_read_b64_tr_b16 v[120:121], v160 offset:30720
	ds_read_b64_tr_b16 v[122:123], v160 offset:32256
	ds_read_b64_tr_b16 v[114:115], v160 offset:32320
	ds_read_b64_tr_b16 v[112:113], v160 offset:30784
	ds_read_b64_tr_b16 v[124:125], v160 offset:33792
	ds_read_b64_tr_b16 v[126:127], v160 offset:35328
	ds_read_b64_tr_b16 v[118:119], v160 offset:35392
	ds_read_b64_tr_b16 v[116:117], v160 offset:33856
	s_waitcnt lgkmcnt(8)
	v_mfma_f32_32x32x16_bf16 v[48:63], v[212:215], v[92:95], v[48:63]
	s_cbranch_scc1 .LBB0_933
	v_cmp_le_u32_e64 s[14:15], v161, v149
	v_cmp_le_u32_e64 s[16:17], v162, v149
	v_cmp_le_u32_e64 s[18:19], v164, v149
	v_cmp_le_u32_e64 s[20:21], v166, v149
	v_cmp_le_u32_e64 s[22:23], v168, v149
	v_cmp_le_u32_e64 s[24:25], v170, v149
	v_cmp_le_u32_e64 s[26:27], v172, v149
	v_cmp_le_u32_e64 s[28:29], v174, v149
	v_cmp_le_u32_e64 s[30:31], v176, v149
	v_cmp_le_u32_e64 s[34:35], v178, v149
	v_cmp_le_u32_e64 s[36:37], v180, v149
	v_cmp_le_u32_e64 s[38:39], v182, v149
	v_cmp_le_u32_e64 s[40:41], v184, v149
	v_cmp_le_u32_e64 s[42:43], v186, v149
	v_cmp_le_u32_e64 s[44:45], v189, v149
	s_and_b64 s[14:15], s[4:5], s[14:15]
	s_and_b64 s[16:17], s[4:5], s[16:17]
	s_and_b64 s[18:19], s[4:5], s[18:19]
	s_and_b64 s[20:21], s[4:5], s[20:21]
	s_and_b64 s[22:23], s[4:5], s[22:23]
	s_and_b64 s[24:25], s[4:5], s[24:25]
	s_and_b64 s[26:27], s[4:5], s[26:27]
	s_and_b64 s[28:29], s[4:5], s[28:29]
	s_and_b64 s[30:31], s[4:5], s[30:31]
	s_and_b64 s[34:35], s[4:5], s[34:35]
	s_and_b64 s[36:37], s[4:5], s[36:37]
	s_and_b64 s[38:39], s[4:5], s[38:39]
	s_and_b64 s[40:41], s[4:5], s[40:41]
	s_and_b64 s[42:43], s[4:5], s[42:43]
	s_and_b64 s[44:45], s[4:5], s[44:45]
	v_cmp_gt_u32_e64 s[46:47], v191, v149
	v_cmp_le_u32_e32 vcc, v138, v149
	v_cndmask_b32_e64 v48, v210, v48, s[14:15]
	v_cmp_lt_u32_e64 s[14:15], v138, v149
	v_cndmask_b32_e64 v49, v210, v49, s[16:17]
	v_cmp_le_u32_e64 s[16:17], v163, v149
	v_cndmask_b32_e64 v50, v210, v50, s[18:19]
	v_cmp_le_u32_e64 s[18:19], v165, v149
	v_cndmask_b32_e64 v51, v210, v51, s[20:21]
	v_cmp_le_u32_e64 s[20:21], v167, v149
	v_cndmask_b32_e64 v52, v210, v52, s[22:23]
	v_cmp_le_u32_e64 s[22:23], v169, v149
	v_cndmask_b32_e64 v53, v210, v53, s[24:25]
	v_cmp_le_u32_e64 s[24:25], v171, v149
	v_cndmask_b32_e64 v54, v210, v54, s[26:27]
	v_cmp_le_u32_e64 s[26:27], v173, v149
	v_cndmask_b32_e64 v55, v210, v55, s[28:29]
	v_cmp_le_u32_e64 s[28:29], v175, v149
	v_cndmask_b32_e64 v56, v210, v56, s[30:31]
	v_cmp_le_u32_e64 s[30:31], v177, v149
	v_cndmask_b32_e64 v57, v210, v57, s[34:35]
	v_cmp_le_u32_e64 s[34:35], v179, v149
	v_cndmask_b32_e64 v58, v210, v58, s[36:37]
	v_cmp_le_u32_e64 s[36:37], v181, v149
	v_cndmask_b32_e64 v59, v210, v59, s[38:39]
	v_cmp_le_u32_e64 s[38:39], v183, v149
	v_cndmask_b32_e64 v60, v210, v60, s[40:41]
	v_cmp_le_u32_e64 s[40:41], v185, v149
	v_cndmask_b32_e64 v61, v210, v61, s[42:43]
	v_cmp_le_u32_e64 s[42:43], v187, v149
	v_cndmask_b32_e64 v62, v210, v62, s[44:45]
	v_cmp_le_u32_e64 s[44:45], v190, v149
	s_or_b64 s[50:51], s[50:51], s[46:47]
	s_and_saveexec_b64 s[46:47], s[50:51]
	v_mov_b32_e32 v63, s33
	s_or_b64 exec, exec, s[46:47]
	s_and_b64 vcc, s[4:5], vcc
	v_cndmask_b32_e32 v64, v210, v64, vcc
	s_and_b64 vcc, s[4:5], s[14:15]
	v_cndmask_b32_e32 v65, v210, v65, vcc
	s_and_b64 vcc, s[4:5], s[16:17]
	v_cndmask_b32_e32 v66, v210, v66, vcc
	s_and_b64 vcc, s[4:5], s[18:19]
	v_cndmask_b32_e32 v67, v210, v67, vcc
	s_and_b64 vcc, s[4:5], s[20:21]
	v_cndmask_b32_e32 v68, v210, v68, vcc
	s_and_b64 vcc, s[4:5], s[22:23]
	v_cndmask_b32_e32 v69, v210, v69, vcc
	s_and_b64 vcc, s[4:5], s[24:25]
	v_cndmask_b32_e32 v70, v210, v70, vcc
	s_and_b64 vcc, s[4:5], s[26:27]
	v_cndmask_b32_e32 v71, v210, v71, vcc
	s_and_b64 vcc, s[4:5], s[28:29]
	v_cndmask_b32_e32 v72, v210, v72, vcc
	s_and_b64 vcc, s[4:5], s[30:31]
	v_cndmask_b32_e32 v73, v210, v73, vcc
	s_and_b64 vcc, s[4:5], s[34:35]
	v_cndmask_b32_e32 v74, v210, v74, vcc
	s_and_b64 vcc, s[4:5], s[36:37]
	v_cndmask_b32_e32 v75, v210, v75, vcc
	s_and_b64 vcc, s[4:5], s[38:39]
	v_cndmask_b32_e32 v76, v210, v76, vcc
	s_and_b64 vcc, s[4:5], s[40:41]
	v_cndmask_b32_e32 v77, v210, v77, vcc
	s_and_b64 vcc, s[4:5], s[42:43]
	v_cndmask_b32_e32 v78, v210, v78, vcc
	s_and_b64 vcc, s[4:5], s[44:45]
	v_cndmask_b32_e32 v79, v210, v79, vcc
	s_branch .LBB0_933
.Lmo_resc:
	v_max_f32_e32 v32, v149, v149
	v_max_f32_e32 v34, 0, v32
	v_exp_f32_e64 v36, -v34
	v_add_f32_e32 v148, v148, v34
	v_xor_b32_e32 v32, 0x80000000, v148
	v_pk_add_f32 v[64:65], v[64:65], v[34:35] op_sel_hi:[1,0] neg_lo:[0,1] neg_hi:[0,1]
	v_mul_f32_e32 v147, v147, v36
	v_pk_add_f32 v[48:49], v[48:49], v[34:35] op_sel_hi:[1,0] neg_lo:[0,1] neg_hi:[0,1]
	v_pk_add_f32 v[66:67], v[66:67], v[34:35] op_sel_hi:[1,0] neg_lo:[0,1] neg_hi:[0,1]
	v_pk_add_f32 v[50:51], v[50:51], v[34:35] op_sel_hi:[1,0] neg_lo:[0,1] neg_hi:[0,1]
	v_pk_add_f32 v[68:69], v[68:69], v[34:35] op_sel_hi:[1,0] neg_lo:[0,1] neg_hi:[0,1]
	v_pk_add_f32 v[52:53], v[52:53], v[34:35] op_sel_hi:[1,0] neg_lo:[0,1] neg_hi:[0,1]
	v_pk_add_f32 v[70:71], v[70:71], v[34:35] op_sel_hi:[1,0] neg_lo:[0,1] neg_hi:[0,1]
	v_pk_add_f32 v[54:55], v[54:55], v[34:35] op_sel_hi:[1,0] neg_lo:[0,1] neg_hi:[0,1]
	v_pk_add_f32 v[72:73], v[72:73], v[34:35] op_sel_hi:[1,0] neg_lo:[0,1] neg_hi:[0,1]
	v_pk_add_f32 v[56:57], v[56:57], v[34:35] op_sel_hi:[1,0] neg_lo:[0,1] neg_hi:[0,1]
	v_pk_add_f32 v[74:75], v[74:75], v[34:35] op_sel_hi:[1,0] neg_lo:[0,1] neg_hi:[0,1]
	v_pk_add_f32 v[58:59], v[58:59], v[34:35] op_sel_hi:[1,0] neg_lo:[0,1] neg_hi:[0,1]
	v_pk_add_f32 v[76:77], v[76:77], v[34:35] op_sel_hi:[1,0] neg_lo:[0,1] neg_hi:[0,1]
	v_pk_add_f32 v[60:61], v[60:61], v[34:35] op_sel_hi:[1,0] neg_lo:[0,1] neg_hi:[0,1]
	v_pk_add_f32 v[78:79], v[78:79], v[34:35] op_sel_hi:[1,0] neg_lo:[0,1] neg_hi:[0,1]
	v_pk_add_f32 v[62:63], v[62:63], v[34:35] op_sel_hi:[1,0] neg_lo:[0,1] neg_hi:[0,1]
	v_pk_mul_f32 v[14:15], v[14:15], v[36:37] op_sel_hi:[1,0]
	v_pk_mul_f32 v[12:13], v[12:13], v[36:37] op_sel_hi:[1,0]
	v_pk_mul_f32 v[10:11], v[10:11], v[36:37] op_sel_hi:[1,0]
	v_pk_mul_f32 v[8:9], v[8:9], v[36:37] op_sel_hi:[1,0]
	v_pk_mul_f32 v[6:7], v[6:7], v[36:37] op_sel_hi:[1,0]
	v_pk_mul_f32 v[4:5], v[4:5], v[36:37] op_sel_hi:[1,0]
	v_pk_mul_f32 v[2:3], v[2:3], v[36:37] op_sel_hi:[1,0]
	v_pk_mul_f32 v[0:1], v[0:1], v[36:37] op_sel_hi:[1,0]
	v_pk_mul_f32 v[30:31], v[30:31], v[36:37] op_sel_hi:[1,0]
	v_pk_mul_f32 v[28:29], v[28:29], v[36:37] op_sel_hi:[1,0]
	v_pk_mul_f32 v[26:27], v[26:27], v[36:37] op_sel_hi:[1,0]
	v_pk_mul_f32 v[24:25], v[24:25], v[36:37] op_sel_hi:[1,0]
	v_pk_mul_f32 v[22:23], v[22:23], v[36:37] op_sel_hi:[1,0]
	v_pk_mul_f32 v[20:21], v[20:21], v[36:37] op_sel_hi:[1,0]
	v_pk_mul_f32 v[18:19], v[18:19], v[36:37] op_sel_hi:[1,0]
	v_pk_mul_f32 v[16:17], v[16:17], v[36:37] op_sel_hi:[1,0]
	v_mov_b32_e32 v33, v32
	v_mov_b32_e32 v34, v32
	v_mov_b32_e32 v35, v32
	v_mov_b32_e32 v36, v32
	v_mov_b32_e32 v37, v32
	v_mov_b32_e32 v38, v32
	v_mov_b32_e32 v39, v32
	v_mov_b32_e32 v40, v32
	v_mov_b32_e32 v41, v32
	v_mov_b32_e32 v42, v32
	v_mov_b32_e32 v43, v32
	v_mov_b32_e32 v44, v32
	v_mov_b32_e32 v45, v32
	v_mov_b32_e32 v46, v32
	v_mov_b32_e32 v47, v32
	s_branch .LBB0_935
